# grid barrier: XCD leader also invalidates before the release (no post-release invalidate anywhere)
# baseline (speedup 1.0000x reference)
.LBB0_958:
	s_mov_b64 s[4:5], exec
	buffer_wbl2 sc1
	buffer_inv sc1
	s_waitcnt lgkmcnt(0)
	s_waitcnt vmcnt(0)
	v_mbcnt_lo_u32_b32 v0, s4, 0
	v_mbcnt_hi_u32_b32 v0, s5, v0
	v_cmp_eq_u32_e32 vcc, 0, v0
	s_and_saveexec_b64 s[6:7], vcc
	s_cbranch_execz .LBB0_960
	s_bcnt1_i32_b64 s4, s[4:5]
	v_mov_b32_e32 v3, s4
	v_mov_b32_e32 v4, 0x1efc3000
	global_atomic_add v3, v4, v3, s[54:55] offset:1024 sc0

.LBB0_974:
	s_or_b64 exec, exec, s[4:5]
	s_mov_b64 s[4:5], exec
	v_mbcnt_lo_u32_b32 v0, s4, 0
	v_mbcnt_hi_u32_b32 v0, s5, v0
	v_cmp_eq_u32_e32 vcc, 0, v0
	s_waitcnt vmcnt(0)
	s_and_saveexec_b64 s[6:7], vcc
	s_cbranch_execnz .LBB0_975
	s_getpc_b64 s[98:99]
